# v1 plus padding: attention steady-loop head at 56 mod 64, later phases as v1 mod 64
# speedup vs baseline: 1.0131x; 1.0102x over previous
; #define WAIT_BAR(N) asm volatile("s_waitcnt vmcnt(" #N ") lgkmcnt(0)\n\ts_barrier":::"memory")
;   #define DMA_K(t,slot) glds16(ksrc+(long)(t)*KVBLK*DM,(unsigned)__builtin_amdgcn_readfirstlane(kdst+(slot)))
;   #define DMA_V(t,slot) do{ glds16(vsrc+(long)(t)*KVBLK*DM,(unsigned)__builtin_amdgcn_readfirstlane(vdst+(slot))); glds16(vsrc+64+(long)(t)*KVBLK*DM,(unsigned)__builtin_amdgcn_readfirstlane(vdst2+(slot))); }while(0)
;   #define CMASK(P0,P1,t) do{int jb_=(t)-(NT-4); if(jb_>=0)cmask(P0,P1,jb_,qrel,hi);}while(0)
;   #define START(P0,P1) do{ resc=false; \
;     { _Pragma("unroll") for(int r=0;r<16;++r){P0[r]=fsub_s(P0[r],mhat);P1[r]=fsub_s(P1[r],mhat);} \
;       } \
;     _Pragma("unroll") for(int r=0;r<16;++r)P0[r]=__builtin_amdgcn_exp2f(P0[r]); }while(0)
;   #define ROT() do{sl_prev=sl_cur;sl_cur=sl_next;sl_next=(sl_next==(NSLOT-1)*SLOTB)?0:sl_next+SLOTB;}while(0)
;   #define CMASK(P0,P1,t) do{}while(0)
;   #define CMASK(P0,P1,t) do{int jb_=(t)-(NT-4); if(jb_>=0)cmask(P0,P1,jb_,qrel,hi);}while(0)
; template<int THRL> __device__ __forceinline__ void attn_unit(int b,int h,int qb,unsigned char*wsb,char*shm,float kmax,const int CMB,float lam){
;     ...
;   const float mhat=sqrtf(q2_)*kmax*1.004f+0.02f;
;   float l_reg=0.f;f32x16 o[2];o[0]=f32x16{};o[1]=f32x16{};f32x16 o2[2];o2[0]=f32x16{};o2[1]=f32x16{};const f32x16 negm=f32x16{};
;   const int qrel=wid*QBLK+r32;
;     ...
;   bool resc=false;
;     ...
;   f32x16 pA0,pA1,pB0,pB1;
;   int sl_prev=0,sl_cur=0,sl_next=SLOTB;
;     ...
;   DMA_K(2,2*SLOTB);
;   WAIT_BAR(4);
;   qkt(pA0,pA1,Kbase,qr,negm,r32,hi);asm volatile("s_nop 15\n\ts_nop 7":"+v"(pA0),"+v"(pA1));CMASK(pA0,pA1,0);
;   START(pA0,pA1);
;   _Pragma("unroll") for(int r=0;r<16;++r)pA1[r]=__builtin_amdgcn_exp2f(pA1[r]);
;   WAIT_BAR(0);
;   DMA_K(3,0);DMA_V(1,SLOTB);
;   ROT();
;   kload8(kf,kp0+sl_cur);
;   WAIT_BAR(3);
; __global__ void __launch_bounds__(NTHR, 2) fwd_megakernel(Args args_unused) {
;     ...
;                     const float kmax = 1.01f * sqrtf(__uint_as_float(__builtin_amdgcn_readfirstlane(__hip_atomic_load((unsigned*)(ws + WS_KMAX) + 2 * bh, __ATOMIC_RELAXED, __HIP_MEMORY_SCOPE_AGENT)))
;                                                    + __uint_as_float(__builtin_amdgcn_readfirstlane(__hip_atomic_load((unsigned*)(ws + WS_KMAX) + 2 * bh + 1, __ATOMIC_RELAXED, __HIP_MEMORY_SCOPE_AGENT))));
.LBB0_309:
	v_mov_b32_e32 v39, s6
	v_add_f32_e32 v39, s5, v39
	v_mul_f32_e32 v40, 0x4f800000, v39
	v_cmp_gt_f32_e32 vcc, s74, v39
	v_add_f32_e32 v37, v37, v38
	v_mul_f32_e32 v38, 0x4f800000, v37
	v_cndmask_b32_e32 v39, v39, v40, vcc
	v_sqrt_f32_e32 v40, v39
	s_waitcnt vmcnt(0) lgkmcnt(0)
	s_barrier
	s_cmp_lg_u32 0, -1
	s_mov_b32 s37, 0
	v_add_u32_e32 v41, -1, v40
	v_fma_f32 v42, -v41, v40, v39
	v_cmp_ge_f32_e64 s[4:5], 0, v42
	v_add_u32_e32 v42, 1, v40
	s_mov_b32 s6, 1
	v_cndmask_b32_e64 v41, v40, v41, s[4:5]
	v_fma_f32 v40, -v42, v40, v39
	v_cmp_lt_f32_e64 s[4:5], 0, v40
	s_nop 1
	v_cndmask_b32_e64 v40, v41, v42, s[4:5]
	v_mul_f32_e32 v41, 0x37800000, v40
	v_cndmask_b32_e32 v40, v40, v41, vcc
	v_cmp_class_f32_e32 vcc, v39, v237
	s_nop 1
	v_cndmask_b32_e32 v39, v40, v39, vcc
	v_cmp_gt_f32_e32 vcc, s74, v37
	v_lshlrev_b32_e32 v40, 1, v36
	v_and_b32_e32 v251, 32, v40
	v_cndmask_b32_e32 v37, v37, v38, vcc
	v_sqrt_f32_e32 v38, v37
	v_lshlrev_b32_e32 v40, 4, v36
	v_and_b32_e32 v40, 0xc0, v40
	v_lshl_or_b32 v246, v242, 8, v40
	v_add_u32_e32 v40, 0, v251
	v_add3_u32 v252, v40, v249, v246
	v_add_u32_e32 v40, -1, v38
	v_fma_f32 v41, -v40, v38, v37
	v_cmp_ge_f32_e64 s[4:5], 0, v41
	v_add_u32_e32 v41, 1, v38
	v_mul_f32_e32 v39, 0x3f8147ae, v39
	v_cndmask_b32_e64 v40, v38, v40, s[4:5]
	v_fma_f32 v38, -v41, v38, v37
	v_cmp_lt_f32_e64 s[4:5], 0, v38
	s_nop 1
	v_cndmask_b32_e64 v38, v40, v41, s[4:5]
	v_mul_f32_e32 v40, 0x37800000, v38
	v_cndmask_b32_e32 v38, v38, v40, vcc
	v_cmp_class_f32_e32 vcc, v37, v237
	s_mov_b64 s[4:5], 0x60000
	s_nop 0
	v_cndmask_b32_e32 v37, v38, v37, vcc
	v_mul_f32_e32 v37, v39, v37
	v_fmamk_f32 v247, v37, 0x3f808312, v238
	v_sub_f32_e32 v0, v0, v247
	v_sub_f32_e32 v1, v1, v247
	v_sub_f32_e32 v16, v16, v247
	v_sub_f32_e32 v17, v17, v247
	v_sub_f32_e32 v2, v2, v247
	v_sub_f32_e32 v18, v18, v247
	s_nop 0
	v_exp_f32_e32 v96, v0
	v_exp_f32_e32 v97, v1
	v_lshl_add_u64 v[0:1], v[32:33], 0, s[4:5]
	s_mov_b32 s4, m0
	s_mov_b32 m0, s3
	s_nop 0
	global_load_lds_dwordx4 v[0:1], off
	s_mov_b32 m0, s4
	s_mov_b64 s[4:5], 0x20000
	v_lshl_add_u64 v[0:1], v[34:35], 0, s[4:5]
	s_cselect_b32 s4, 0, 0
	s_add_i32 s1, s4, s1
	s_add_i32 s4, s1, 0x8000
	s_mov_b32 s5, m0
	s_mov_b32 m0, s4
	s_nop 0
	global_load_lds_dwordx4 v[0:1], off
	s_mov_b32 m0, s5
	s_mov_b64 s[4:5], 0x20080
	v_lshl_add_u64 v[0:1], v[34:35], 0, s[4:5]
	s_add_i32 s1, s1, 0xe000
	s_mov_b32 s4, m0
	s_mov_b32 m0, s1
	s_nop 0
	global_load_lds_dwordx4 v[0:1], off
	s_mov_b32 m0, s4
	ds_read_b128 v[204:207], v250 offset:8192
	ds_read_b128 v[200:203], v250 offset:8704
	ds_read_b128 v[196:199], v250 offset:10240
	ds_read_b128 v[192:195], v250 offset:10752
	ds_read_b128 v[188:191], v250 offset:12288
	ds_read_b128 v[184:187], v250 offset:12800
	ds_read_b128 v[180:183], v250 offset:14336
	ds_read_b128 v[176:179], v250 offset:14848
	v_sub_f32_e32 v3, v3, v247
	v_sub_f32_e32 v19, v19, v247
	v_sub_f32_e32 v4, v4, v247
	v_sub_f32_e32 v20, v20, v247
	v_sub_f32_e32 v5, v5, v247
	v_sub_f32_e32 v21, v21, v247
	v_sub_f32_e32 v6, v6, v247
	v_sub_f32_e32 v22, v22, v247
	v_sub_f32_e32 v7, v7, v247
	v_sub_f32_e32 v23, v23, v247
	v_sub_f32_e32 v8, v8, v247
	v_sub_f32_e32 v24, v24, v247
	v_sub_f32_e32 v9, v9, v247
	v_sub_f32_e32 v25, v25, v247
	v_sub_f32_e32 v10, v10, v247
	v_sub_f32_e32 v26, v26, v247
	v_sub_f32_e32 v11, v11, v247
	v_sub_f32_e32 v27, v27, v247
	v_sub_f32_e32 v12, v12, v247
	v_sub_f32_e32 v28, v28, v247
	v_sub_f32_e32 v13, v13, v247
	v_sub_f32_e32 v29, v29, v247
	v_sub_f32_e32 v14, v14, v247
	v_sub_f32_e32 v30, v30, v247
	v_sub_f32_e32 v15, v15, v247
	v_sub_f32_e32 v31, v31, v247
	v_exp_f32_e32 v98, v2
	v_exp_f32_e32 v99, v3
	v_exp_f32_e32 v100, v4
	v_exp_f32_e32 v101, v5
	v_exp_f32_e32 v102, v6
	v_exp_f32_e32 v103, v7
	v_exp_f32_e32 v104, v8
	v_exp_f32_e32 v105, v9
	v_exp_f32_e32 v106, v10
	v_exp_f32_e32 v107, v11
	v_exp_f32_e32 v108, v12
	v_exp_f32_e32 v109, v13
	v_exp_f32_e32 v110, v14
	v_exp_f32_e32 v111, v15
	v_exp_f32_e32 v80, v16
	v_exp_f32_e32 v81, v17
	v_exp_f32_e32 v82, v18
	v_exp_f32_e32 v83, v19
	v_exp_f32_e32 v84, v20
	v_exp_f32_e32 v85, v21
	v_exp_f32_e32 v86, v22
	v_exp_f32_e32 v87, v23
	v_exp_f32_e32 v88, v24
	v_exp_f32_e32 v89, v25
	v_exp_f32_e32 v90, v26
	v_exp_f32_e32 v91, v27
	v_exp_f32_e32 v92, v28
	v_exp_f32_e32 v93, v29
	v_exp_f32_e32 v94, v30
	v_exp_f32_e32 v95, v31
	s_waitcnt vmcnt(3) lgkmcnt(0)
	s_barrier
	v_and_b32_e32 v0, 3, v36
	s_andn2_b64 vcc, exec, s[54:55]
	v_lshlrev_b32_e32 v208, 4, v0
	s_cbranch_vccnz .LBB0_313
; template<int THRL> __device__ __forceinline__ void attn_unit(int b,int h,int qb,unsigned char*wsb,char*shm,float kmax,const int CMB,float lam){
;     ...
;   float l_reg=0.f;f32x16 o[2];o[0]=f32x16{};o[1]=f32x16{};f32x16 o2[2];o2[0]=f32x16{};o2[1]=f32x16{};const f32x16 negm=f32x16{};
;   const int qrel=wid*QBLK+r32;
;     ...
;   bool resc=false;
;     ...
;   f32x16 pA0,pA1,pB0,pB1;
;   int sl_prev=0,sl_cur=0,sl_next=SLOTB;
	s_lshl_b32 s1, s43, 6
	s_add_i32 s6, s79, s1
	s_lshr_b32 s4, s6, 7
	s_mov_b32 s5, s7
	s_lshl_b64 s[4:5], s[4:5], 8
	s_lshl_b64 s[36:37], s[68:69], 1
	s_add_u32 s4, s36, s4
	v_mov_b32_e32 v209, v221
	s_addc_u32 s5, s37, s5
	s_lshl_b32 s1, s95, 9
	v_lshl_add_u64 v[0:1], s[4:5], 0, v[208:209]
	s_and_b32 s1, s1, 0x18000
	s_lshl_b64 s[4:5], s[66:67], 1
	s_lshl_b64 s[36:37], s[6:7], 1
	v_lshl_or_b32 v2, v214, 11, s1
	s_add_u32 s1, s64, s36
	s_addc_u32 s6, s65, s37
	v_mov_b32_e32 v3, v221
	s_add_u32 s4, s1, s4
	v_lshl_add_u64 v[0:1], v[0:1], 0, v[2:3]
	s_addc_u32 s5, s6, s5
	v_mov_b32_e32 v64, 0
	s_mov_b32 s33, 6
	v_lshl_add_u64 v[210:211], s[64:65], 0, v[0:1]
	v_lshl_add_u64 v[212:213], s[4:5], 0, v[220:221]
	s_movk_i32 s36, 0x4000
	s_movk_i32 s42, 0x2000
	s_mov_b32 s5, 0
	v_mov_b32_e32 v0, 0
	v_mov_b32_e32 v1, v64
	v_mov_b32_e32 v2, v64
	v_mov_b32_e32 v3, v64
	v_mov_b32_e32 v4, v64
	v_mov_b32_e32 v5, v64
	v_mov_b32_e32 v6, v64
	v_mov_b32_e32 v7, v64
	v_mov_b32_e32 v8, v64
	v_mov_b32_e32 v9, v64
	v_mov_b32_e32 v10, v64
	v_mov_b32_e32 v11, v64
	v_mov_b32_e32 v12, v64
	v_mov_b32_e32 v13, v64
	v_mov_b32_e32 v14, v64
	v_mov_b32_e32 v15, v64
	v_mov_b32_e32 v16, 0
	v_mov_b32_e32 v17, v64
	v_mov_b32_e32 v18, v64
	v_mov_b32_e32 v19, v64
	v_mov_b32_e32 v20, v64
	v_mov_b32_e32 v21, v64
	v_mov_b32_e32 v22, v64
	v_mov_b32_e32 v23, v64
	v_mov_b32_e32 v24, v64
	v_mov_b32_e32 v25, v64
	v_mov_b32_e32 v26, v64
	v_mov_b32_e32 v27, v64
	v_mov_b32_e32 v28, v64
	v_mov_b32_e32 v29, v64
	v_mov_b32_e32 v30, v64
	v_mov_b32_e32 v31, v64
	v_mov_b32_e32 v32, 0
	v_mov_b32_e32 v33, v64
	v_mov_b32_e32 v34, v64
	v_mov_b32_e32 v35, v64
	v_mov_b32_e32 v36, v64
	v_mov_b32_e32 v37, v64
	v_mov_b32_e32 v38, v64
	v_mov_b32_e32 v39, v64
	v_mov_b32_e32 v40, v64
	v_mov_b32_e32 v41, v64
	v_mov_b32_e32 v42, v64
	v_mov_b32_e32 v43, v64
	v_mov_b32_e32 v44, v64
	v_mov_b32_e32 v45, v64
	v_mov_b32_e32 v46, v64
	v_mov_b32_e32 v47, v64
	v_mov_b32_e32 v48, 0
	v_mov_b32_e32 v49, v64
	v_mov_b32_e32 v50, v64
	v_mov_b32_e32 v51, v64
	v_mov_b32_e32 v52, v64
	v_mov_b32_e32 v53, v64
	v_mov_b32_e32 v54, v64
	v_mov_b32_e32 v55, v64
	v_mov_b32_e32 v56, v64
	v_mov_b32_e32 v57, v64
	v_mov_b32_e32 v58, v64
	v_mov_b32_e32 v59, v64
	v_mov_b32_e32 v60, v64
	v_mov_b32_e32 v61, v64
	v_mov_b32_e32 v62, v64
	v_mov_b32_e32 v63, v64
	v_lshlrev_b32_e32 v143, 2, v230
	v_add_u32_e32 v143, 0x12800, v143
	ds_write_b32 v143, v246 offset:32768
	ds_write_b32 v143, v230
	ds_write_b32 v143, v231 offset:2048
	ds_write_b32 v143, v232 offset:4096
	ds_write_b32 v143, v233 offset:6144
	ds_write_b32 v143, v234 offset:8192
	ds_write_b32 v143, v235 offset:10240
	ds_write_b32 v143, v236 offset:12288
	ds_write_b32 v143, v237 offset:14336
	ds_write_b32 v143, v238 offset:16384
	ds_write_b32 v143, v239 offset:18432
	ds_write_b32 v143, v240 offset:20480
	ds_write_b32 v143, v241 offset:22528
	ds_write_b32 v143, v242 offset:24576
	ds_write_b32 v143, v243 offset:26624
	ds_write_b32 v143, v244 offset:28672
	ds_write_b32 v143, v245 offset:30720
	v_mov_b32_e32 v246, v143
	v_xor_b32_e32 v230, 0x80000000, v247
	v_mov_b32_e32 v231, v230
	v_mov_b32_e32 v232, v230
	v_mov_b32_e32 v233, v230
	v_mov_b32_e32 v234, v230
	v_mov_b32_e32 v235, v230
	v_mov_b32_e32 v236, v230
	v_mov_b32_e32 v237, v230
	v_mov_b32_e32 v238, v230
	v_mov_b32_e32 v239, v230
	v_mov_b32_e32 v240, v230
	v_mov_b32_e32 v241, v230
	v_mov_b32_e32 v242, v230
	v_mov_b32_e32 v243, v230
	v_mov_b32_e32 v244, v230
	v_mov_b32_e32 v245, v230
	s_waitcnt lgkmcnt(0)
	s_nop 0
	s_nop 0
	s_nop 0
	s_nop 0
.LBB0_311:
	s_mov_b32 s37, s36
	s_mov_b32 s4, s33
	s_mov_b32 s1, s42
	v_add_u32_e32 v209, s5, v252
	ds_read_b64_tr_b16 v[216:217], v209 offset:24576
	ds_read_b64_tr_b16 v[218:219], v209 offset:25088
	v_add_f32_e32 v65, v96, v97
	v_add_f32_e32 v65, v98, v65
	v_add_f32_e32 v65, v99, v65
	v_add_f32_e32 v65, v100, v65
	v_add_f32_e32 v65, v101, v65
	v_cvt_pk_bf16_f32 v172, v96, v97
	v_cvt_pk_bf16_f32 v173, v98, v99
	s_waitcnt lgkmcnt(9)
	v_mfma_f32_32x32x16_bf16 v[128:143], v[204:207], v[156:159], v[230:245]
	ds_read_b64_tr_b16 v[204:205], v209 offset:28672
	ds_read_b64_tr_b16 v[206:207], v209 offset:29184
	v_add_f32_e32 v65, v102, v65
	v_add_f32_e32 v65, v103, v65
	v_add_f32_e32 v65, v104, v65
	v_add_f32_e32 v65, v105, v65
	v_cvt_pk_bf16_f32 v174, v100, v101
	v_cvt_pk_bf16_f32 v175, v102, v103
	s_waitcnt lgkmcnt(10)
	v_mfma_f32_32x32x16_bf16 v[112:127], v[200:203], v[156:159], v[230:245]
	ds_read_b64_tr_b16 v[74:75], v209 offset:25600
	ds_read_b64_tr_b16 v[76:77], v209 offset:26112
	v_add_f32_e32 v65, v106, v65
	v_add_f32_e32 v65, v107, v65
	v_add_f32_e32 v65, v108, v65
	v_add_f32_e32 v65, v109, v65
	v_cvt_pk_bf16_f32 v168, v104, v105
	v_cvt_pk_bf16_f32 v169, v106, v107
	s_waitcnt lgkmcnt(11)
	v_mfma_f32_32x32x16_bf16 v[128:143], v[196:199], v[152:155], v[128:143]
	ds_read_b64_tr_b16 v[70:71], v209 offset:29696
	ds_read_b64_tr_b16 v[72:73], v209 offset:30208
	v_add_f32_e32 v65, v110, v65
	v_add_f32_e32 v65, v111, v65
	v_add_f32_e32 v65, v80, v65
	v_add_f32_e32 v65, v81, v65
	v_cvt_pk_bf16_f32 v170, v108, v109
	v_cvt_pk_bf16_f32 v171, v110, v111
	s_waitcnt lgkmcnt(12)
	v_mfma_f32_32x32x16_bf16 v[112:127], v[192:195], v[152:155], v[112:127]
	ds_read_b64_tr_b16 v[66:67], v209 offset:26624
	ds_read_b64_tr_b16 v[68:69], v209 offset:27136
	v_add_f32_e32 v65, v82, v65
	v_add_f32_e32 v65, v83, v65
	v_add_f32_e32 v65, v84, v65
	v_add_f32_e32 v65, v85, v65
	v_cvt_pk_bf16_f32 v164, v80, v81
	v_cvt_pk_bf16_f32 v165, v82, v83
	s_waitcnt lgkmcnt(13)
	v_mfma_f32_32x32x16_bf16 v[128:143], v[188:191], v[148:151], v[128:143]
	ds_read_b64_tr_b16 v[100:101], v209 offset:30720
	ds_read_b64_tr_b16 v[102:103], v209 offset:31232
	v_add_f32_e32 v65, v86, v65
	v_add_f32_e32 v65, v87, v65
	v_add_f32_e32 v65, v88, v65
	v_add_f32_e32 v65, v89, v65
	v_cvt_pk_bf16_f32 v166, v84, v85
	v_cvt_pk_bf16_f32 v167, v86, v87
	s_waitcnt lgkmcnt(14)
	v_mfma_f32_32x32x16_bf16 v[112:127], v[184:187], v[148:151], v[112:127]
	ds_read_b64_tr_b16 v[96:97], v209 offset:27648
	ds_read_b64_tr_b16 v[98:99], v209 offset:28160
	v_add_f32_e32 v65, v90, v65
	v_add_f32_e32 v65, v91, v65
	v_add_f32_e32 v65, v92, v65
	v_add_f32_e32 v65, v93, v65
	v_cvt_pk_bf16_f32 v160, v88, v89
	v_cvt_pk_bf16_f32 v161, v90, v91
	s_waitcnt lgkmcnt(14)
	v_mfma_f32_32x32x16_bf16 v[128:143], v[180:183], v[144:147], v[128:143]
	ds_read_b64_tr_b16 v[86:87], v209 offset:31744
	ds_read_b64_tr_b16 v[88:89], v209 offset:32256
	v_add_f32_e32 v65, v94, v65
	v_add_f32_e32 v65, v95, v65
	v_add_f32_e32 v65, 0, v65
	v_cvt_pk_bf16_f32 v162, v92, v93
	v_cvt_pk_bf16_f32 v163, v94, v95
	v_mfma_f32_32x32x16_bf16 v[112:127], v[176:179], v[144:147], v[112:127]
	v_lshl_add_u64 v[190:191], v[212:213], 0, s[48:49]
	v_lshl_add_u64 v[78:79], v[190:191], 0, s[10:11]
	s_add_i32 s5, s42, s3
	s_mov_b32 s6, m0
	s_mov_b32 m0, s5
	s_nop 0
	global_load_lds_dwordx4 v[78:79], off
	s_mov_b32 m0, s6
	v_lshl_add_u64 v[188:189], v[210:211], 0, s[48:49]
	v_lshl_add_u64 v[78:79], v[188:189], 0, s[12:13]
	s_add_i32 s5, s36, s97
	s_mov_b32 s6, m0
	s_mov_b32 m0, s5
	s_nop 0
	global_load_lds_dwordx4 v[78:79], off
	s_mov_b32 m0, s6
	v_lshl_add_u64 v[78:79], v[188:189], 0, s[14:15]
	s_add_i32 s5, s36, s96
	s_mov_b32 s6, m0
	s_mov_b32 m0, s5
	s_nop 0
	global_load_lds_dwordx4 v[78:79], off
	s_mov_b32 m0, s6
	s_waitcnt lgkmcnt(14)
	v_mfma_f32_32x32x16_bf16 v[32:47], v[172:175], v[216:219], v[32:47]
	v_exp_f32_e32 v128, v128
	v_exp_f32_e32 v129, v129
	ds_read_b64_tr_b16 v[90:91], v209 offset:49152
	ds_read_b64_tr_b16 v[92:93], v209 offset:49664
	s_waitcnt lgkmcnt(14)
	v_mfma_f32_32x32x16_bf16 v[48:63], v[172:175], v[204:207], v[48:63]
	v_exp_f32_e32 v130, v130
	v_exp_f32_e32 v131, v131
	ds_read_b64_tr_b16 v[104:105], v209 offset:53248
	ds_read_b64_tr_b16 v[106:107], v209 offset:53760
	v_add_u32_e32 v94, s37, v250
	ds_read_b128 v[82:85], v94
	ds_read_b128 v[78:81], v94 offset:512
	s_waitcnt lgkmcnt(14)
	v_mfma_f32_32x32x16_bf16 v[32:47], v[168:171], v[74:77], v[32:47]
	v_exp_f32_e32 v132, v132
	v_exp_f32_e32 v133, v133
	ds_read_b64_tr_b16 v[108:109], v209 offset:50176
	ds_read_b64_tr_b16 v[110:111], v209 offset:50688
	ds_read_b128 v[184:187], v94 offset:2048
	ds_read_b128 v[176:179], v94 offset:2560
	v_mfma_f32_32x32x16_bf16 v[48:63], v[168:171], v[70:73], v[48:63]
	v_exp_f32_e32 v134, v134
	v_exp_f32_e32 v135, v135
	ds_read_b64_tr_b16 v[192:193], v209 offset:54272
	ds_read_b64_tr_b16 v[194:195], v209 offset:54784
	ds_read_b128 v[180:183], v94 offset:4096
	ds_read_b128 v[70:73], v94 offset:4608
	s_waitcnt lgkmcnt(14)
	v_mfma_f32_32x32x16_bf16 v[32:47], v[164:167], v[66:69], v[32:47]
	v_exp_f32_e32 v136, v136
	v_exp_f32_e32 v137, v137
	ds_read_b64_tr_b16 v[196:197], v209 offset:51200
	ds_read_b64_tr_b16 v[198:199], v209 offset:51712
	ds_read_b128 v[74:77], v94 offset:6144
	ds_read_b128 v[66:69], v94 offset:6656
	v_mfma_f32_32x32x16_bf16 v[48:63], v[164:167], v[100:103], v[48:63]
	v_exp_f32_e32 v138, v138
	v_exp_f32_e32 v139, v139
	ds_read_b64_tr_b16 v[100:101], v209 offset:55296
	ds_read_b64_tr_b16 v[102:103], v209 offset:55808
	v_mfma_f32_32x32x16_bf16 v[32:47], v[160:163], v[96:99], v[32:47]
	v_exp_f32_e32 v140, v140
	v_exp_f32_e32 v141, v141
	ds_read_b64_tr_b16 v[94:95], v209 offset:52224
	ds_read_b64_tr_b16 v[96:97], v209 offset:52736
	v_mfma_f32_32x32x16_bf16 v[48:63], v[160:163], v[86:89], v[48:63]
	v_exp_f32_e32 v142, v142
	v_exp_f32_e32 v143, v143
	ds_read_b64_tr_b16 v[86:87], v209 offset:56320
	ds_read_b64_tr_b16 v[88:89], v209 offset:56832
	s_waitcnt lgkmcnt(14)
	v_mfma_f32_32x32x16_bf16 v[0:15], v[172:175], v[90:93], v[0:15]
	v_exp_f32_e32 v112, v112
	v_exp_f32_e32 v113, v113
	v_mfma_f32_32x32x16_bf16 v[16:31], v[172:175], v[104:107], v[16:31]
	v_exp_f32_e32 v114, v114
	v_exp_f32_e32 v115, v115
	v_mfma_f32_32x32x16_bf16 v[0:15], v[168:171], v[108:111], v[0:15]
	v_exp_f32_e32 v116, v116
	v_exp_f32_e32 v117, v117
	s_waitcnt lgkmcnt(12)
	v_mfma_f32_32x32x16_bf16 v[16:31], v[168:171], v[192:195], v[16:31]
	v_exp_f32_e32 v118, v118
	v_exp_f32_e32 v119, v119
	s_waitcnt lgkmcnt(8)
	v_mfma_f32_32x32x16_bf16 v[0:15], v[164:167], v[196:199], v[0:15]
	v_exp_f32_e32 v120, v120
	v_exp_f32_e32 v121, v121
	s_waitcnt lgkmcnt(4)
	v_mfma_f32_32x32x16_bf16 v[16:31], v[164:167], v[100:103], v[16:31]
	v_exp_f32_e32 v122, v122
	v_exp_f32_e32 v123, v123
	s_waitcnt lgkmcnt(2)
	v_mfma_f32_32x32x16_bf16 v[0:15], v[160:163], v[94:97], v[0:15]
	v_exp_f32_e32 v124, v124
	v_exp_f32_e32 v125, v125
	s_waitcnt lgkmcnt(0)
	v_mfma_f32_32x32x16_bf16 v[16:31], v[160:163], v[86:89], v[16:31]
	v_exp_f32_e32 v126, v126
	v_exp_f32_e32 v127, v127
	s_waitcnt vmcnt(3) lgkmcnt(0)
	s_barrier
; #define WAIT_BAR(N) asm volatile("s_waitcnt vmcnt(" #N ") lgkmcnt(0)\n\ts_barrier":::"memory")
;   #define RESC() do{ if(resc){ asm volatile("s_waitcnt lgkmcnt(0)":::"memory"); \
;       _Pragma("unroll") for(int d_=0;d_<2;++d_) _Pragma("unroll") for(int r=0;r<16;++r){const float f_=wsf[crow(r,hi)];o[d_][r]*=f_;o2[d_][r]*=f_;} } }while(0)
;   #define ROT() do{sl_prev=sl_cur;sl_cur=sl_next;sl_next=(sl_next==(NSLOT-1)*SLOTB)?0:sl_next+SLOTB;}while(0)
; template<int THRL> __device__ __forceinline__ void attn_unit(int b,int h,int qb,unsigned char*wsb,char*shm,float kmax,const int CMB,float lam){
;     ...
;   int t=1;
;     ...
;   for(;t+5<NT;t+=2){
;     STEP(pB0,pB1,pA0,pA1,t,true,true,true);     WAIT_BAR(3); RESC(); ROT();
;     STEP(pA0,pA1,pB0,pB1,t+1,true,true,true);   WAIT_BAR(3); RESC(); ROT();
	s_add_i32 s5, s36, 0x2000
	s_cmpk_lg_i32 s36, 0x4000
	s_cselect_b32 s42, s5, 0
	v_add_u32_e32 v209, s1, v252
	ds_read_b64_tr_b16 v[192:193], v209 offset:24576
	ds_read_b64_tr_b16 v[194:195], v209 offset:25088
	v_mfma_f32_32x32x16_bf16 v[96:111], v[82:85], v[156:159], v[230:245]
	v_add_f32_e32 v86, v128, v129
	v_add_f32_e32 v86, v130, v86
	v_add_f32_e32 v86, v131, v86
	v_add_f32_e32 v86, v132, v86
	v_add_f32_e32 v86, v133, v86
	v_cvt_pk_bf16_f32 v172, v128, v129
	v_cvt_pk_bf16_f32 v173, v130, v131
	ds_read_b64_tr_b16 v[196:197], v209 offset:28672
	ds_read_b64_tr_b16 v[198:199], v209 offset:29184
	v_add_f32_e32 v82, v134, v86
	v_add_f32_e32 v82, v135, v82
	v_add_f32_e32 v82, v136, v82
	v_add_f32_e32 v128, v137, v82
	v_mfma_f32_32x32x16_bf16 v[80:95], v[78:81], v[156:159], v[230:245]
	v_cvt_pk_bf16_f32 v174, v132, v133
	v_cvt_pk_bf16_f32 v175, v134, v135
	ds_read_b64_tr_b16 v[216:217], v209 offset:25600
	ds_read_b64_tr_b16 v[218:219], v209 offset:26112
	v_mfma_f32_32x32x16_bf16 v[96:111], v[184:187], v[152:155], v[96:111]
	v_add_f32_e32 v78, v138, v128
	v_add_f32_e32 v78, v139, v78
	v_add_f32_e32 v78, v140, v78
	v_add_f32_e32 v78, v141, v78
	v_cvt_pk_bf16_f32 v168, v136, v137
	v_cvt_pk_bf16_f32 v169, v138, v139
	ds_read_b64_tr_b16 v[136:137], v209 offset:29696
	ds_read_b64_tr_b16 v[138:139], v209 offset:30208
	v_mfma_f32_32x32x16_bf16 v[80:95], v[176:179], v[152:155], v[80:95]
	v_add_f32_e32 v78, v142, v78
	v_add_f32_e32 v78, v143, v78
	v_add_f32_e32 v78, v112, v78
	v_add_f32_e32 v78, v113, v78
	v_cvt_pk_bf16_f32 v170, v140, v141
	v_cvt_pk_bf16_f32 v171, v142, v143
	ds_read_b64_tr_b16 v[132:133], v209 offset:26624
	ds_read_b64_tr_b16 v[134:135], v209 offset:27136
	v_mfma_f32_32x32x16_bf16 v[96:111], v[180:183], v[148:151], v[96:111]
	v_add_f32_e32 v78, v114, v78
	v_add_f32_e32 v78, v115, v78
	v_add_f32_e32 v78, v116, v78
	v_add_f32_e32 v78, v117, v78
	v_cvt_pk_bf16_f32 v164, v112, v113
	v_cvt_pk_bf16_f32 v165, v114, v115
	ds_read_b64_tr_b16 v[128:129], v209 offset:30720
	ds_read_b64_tr_b16 v[130:131], v209 offset:31232
	v_mfma_f32_32x32x16_bf16 v[80:95], v[70:73], v[148:151], v[80:95]
	v_add_f32_e32 v78, v118, v78
	v_add_f32_e32 v78, v119, v78
	v_add_f32_e32 v78, v120, v78
	v_add_f32_e32 v78, v121, v78
	v_cvt_pk_bf16_f32 v166, v116, v117
	v_cvt_pk_bf16_f32 v167, v118, v119
	ds_read_b64_tr_b16 v[112:113], v209 offset:27648
	ds_read_b64_tr_b16 v[114:115], v209 offset:28160
	v_mfma_f32_32x32x16_bf16 v[96:111], v[74:77], v[144:147], v[96:111]
	v_add_f32_e32 v70, v122, v78
	v_add_f32_e32 v70, v123, v70
	v_add_f32_e32 v70, v124, v70
	v_add_f32_e32 v78, v125, v70
	v_cvt_pk_bf16_f32 v160, v120, v121
	v_cvt_pk_bf16_f32 v161, v122, v123
	ds_read_b64_tr_b16 v[70:71], v209 offset:31744
	ds_read_b64_tr_b16 v[72:73], v209 offset:32256
	v_mfma_f32_32x32x16_bf16 v[80:95], v[66:69], v[144:147], v[80:95]
	v_add_f32_e32 v74, v126, v78
	v_add_f32_e32 v74, v127, v74
	v_add_f32_e32 v74, 0, v74
	v_cvt_pk_bf16_f32 v162, v124, v125
	v_cvt_pk_bf16_f32 v163, v126, v127
	v_lshl_add_u64 v[66:67], v[190:191], 0, s[16:17]
	s_add_i32 s1, s36, s3
	s_mov_b32 s5, m0
	s_mov_b32 m0, s1
	s_nop 0
	global_load_lds_dwordx4 v[66:67], off
	s_mov_b32 m0, s5
	v_lshl_add_u64 v[66:67], v[188:189], 0, s[18:19]
	s_add_i32 s1, s42, s97
	s_mov_b32 s5, m0
	s_mov_b32 m0, s1
	s_nop 0
	global_load_lds_dwordx4 v[66:67], off
	s_mov_b32 m0, s5
	v_lshl_add_u64 v[66:67], v[188:189], 0, s[20:21]
	s_add_i32 s1, s42, s96
	s_mov_b32 s5, m0
	s_mov_b32 m0, s1
	s_nop 0
	global_load_lds_dwordx4 v[66:67], off
	s_mov_b32 m0, s5
	s_waitcnt lgkmcnt(14)
	v_mfma_f32_32x32x16_bf16 v[32:47], v[172:175], v[192:195], v[32:47]
	v_exp_f32_e32 v96, v96
	v_exp_f32_e32 v97, v97
	ds_read_b64_tr_b16 v[66:67], v209 offset:49152
	ds_read_b64_tr_b16 v[68:69], v209 offset:49664
	s_waitcnt lgkmcnt(14)
	v_mfma_f32_32x32x16_bf16 v[48:63], v[172:175], v[196:199], v[48:63]
	v_exp_f32_e32 v98, v98
	v_exp_f32_e32 v99, v99
	ds_read_b64_tr_b16 v[76:77], v209 offset:53248
	ds_read_b64_tr_b16 v[78:79], v209 offset:53760
	v_add_u32_e32 v75, s42, v250
	ds_read_b128 v[204:207], v75
	ds_read_b128 v[200:203], v75 offset:512
	s_waitcnt lgkmcnt(14)
	v_mfma_f32_32x32x16_bf16 v[32:47], v[168:171], v[216:219], v[32:47]
	v_exp_f32_e32 v100, v100
	v_exp_f32_e32 v101, v101
	ds_read_b64_tr_b16 v[116:117], v209 offset:50176
	ds_read_b64_tr_b16 v[118:119], v209 offset:50688
	ds_read_b128 v[196:199], v75 offset:2048
	ds_read_b128 v[192:195], v75 offset:2560
	v_mfma_f32_32x32x16_bf16 v[48:63], v[168:171], v[136:139], v[48:63]
	v_exp_f32_e32 v102, v102
	v_exp_f32_e32 v103, v103
	ds_read_b64_tr_b16 v[120:121], v209 offset:54272
	ds_read_b64_tr_b16 v[122:123], v209 offset:54784
	ds_read_b128 v[188:191], v75 offset:4096
	ds_read_b128 v[184:187], v75 offset:4608
	s_waitcnt lgkmcnt(14)
	v_mfma_f32_32x32x16_bf16 v[32:47], v[164:167], v[132:135], v[32:47]
	v_exp_f32_e32 v104, v104
	v_exp_f32_e32 v105, v105
	ds_read_b64_tr_b16 v[124:125], v209 offset:51200
	ds_read_b64_tr_b16 v[126:127], v209 offset:51712
	ds_read_b128 v[180:183], v75 offset:6144
	ds_read_b128 v[176:179], v75 offset:6656
	v_mfma_f32_32x32x16_bf16 v[48:63], v[164:167], v[128:131], v[48:63]
	v_exp_f32_e32 v106, v106
	v_exp_f32_e32 v107, v107
	ds_read_b64_tr_b16 v[128:129], v209 offset:55296
	ds_read_b64_tr_b16 v[130:131], v209 offset:55808
	v_mfma_f32_32x32x16_bf16 v[32:47], v[160:163], v[112:115], v[32:47]
	v_exp_f32_e32 v108, v108
	v_exp_f32_e32 v109, v109
	ds_read_b64_tr_b16 v[112:113], v209 offset:52224
	ds_read_b64_tr_b16 v[114:115], v209 offset:52736
	v_mfma_f32_32x32x16_bf16 v[48:63], v[160:163], v[70:73], v[48:63]
	v_exp_f32_e32 v110, v110
	v_exp_f32_e32 v111, v111
	ds_read_b64_tr_b16 v[70:71], v209 offset:56320
	ds_read_b64_tr_b16 v[72:73], v209 offset:56832
	s_waitcnt lgkmcnt(14)
	v_mfma_f32_32x32x16_bf16 v[0:15], v[172:175], v[66:69], v[0:15]
	v_exp_f32_e32 v80, v80
	v_exp_f32_e32 v81, v81
	v_mfma_f32_32x32x16_bf16 v[16:31], v[172:175], v[76:79], v[16:31]
	v_exp_f32_e32 v82, v82
	v_exp_f32_e32 v83, v83
	v_mfma_f32_32x32x16_bf16 v[0:15], v[168:171], v[116:119], v[0:15]
	v_exp_f32_e32 v84, v84
	v_exp_f32_e32 v85, v85
	s_waitcnt lgkmcnt(12)
	v_mfma_f32_32x32x16_bf16 v[16:31], v[168:171], v[120:123], v[16:31]
	v_exp_f32_e32 v86, v86
	v_exp_f32_e32 v87, v87
	s_waitcnt lgkmcnt(8)
	v_mfma_f32_32x32x16_bf16 v[0:15], v[164:167], v[124:127], v[0:15]
	v_exp_f32_e32 v88, v88
	v_exp_f32_e32 v89, v89
	s_waitcnt lgkmcnt(4)
	v_mfma_f32_32x32x16_bf16 v[16:31], v[164:167], v[128:131], v[16:31]
	v_exp_f32_e32 v90, v90
	v_exp_f32_e32 v91, v91
	s_waitcnt lgkmcnt(2)
	v_mfma_f32_32x32x16_bf16 v[0:15], v[160:163], v[112:115], v[0:15]
	v_exp_f32_e32 v92, v92
	v_exp_f32_e32 v93, v93
	s_waitcnt lgkmcnt(0)
	v_mfma_f32_32x32x16_bf16 v[16:31], v[160:163], v[70:73], v[16:31]
	v_exp_f32_e32 v94, v94
	v_exp_f32_e32 v95, v95
	s_add_i32 s1, s42, 0x2000
	s_waitcnt vmcnt(3) lgkmcnt(0)
	s_barrier
; #define WAIT_BAR(N) asm volatile("s_waitcnt vmcnt(" #N ") lgkmcnt(0)\n\ts_barrier":::"memory")
;   #define RESC() do{ if(resc){ asm volatile("s_waitcnt lgkmcnt(0)":::"memory"); \
;       _Pragma("unroll") for(int d_=0;d_<2;++d_) _Pragma("unroll") for(int r=0;r<16;++r){const float f_=wsf[crow(r,hi)];o[d_][r]*=f_;o2[d_][r]*=f_;} } }while(0)
;   #define ROT() do{sl_prev=sl_cur;sl_cur=sl_next;sl_next=(sl_next==(NSLOT-1)*SLOTB)?0:sl_next+SLOTB;}while(0)
;   #define ENDW(tt) do{ if((tt)+3<NT){WAIT_BAR(3);} else if((tt)+2<NT){WAIT_BAR(2);} else {WAIT_BAR(0);} }while(0)
; template<int THRL> __device__ __forceinline__ void attn_unit(int b,int h,int qb,unsigned char*wsb,char*shm,float kmax,const int CMB,float lam){
;     ...
;   for(;t+5<NT;t+=2){
;     STEP(pB0,pB1,pA0,pA1,t,true,true,true);     WAIT_BAR(3); RESC(); ROT();
;     STEP(pA0,pA1,pB0,pB1,t+1,true,true,true);   WAIT_BAR(3); RESC(); ROT();
;   }
;     ...
;   for(;t+1<NT;t+=2){
;     STEP(pB0,pB1,pA0,pA1,t,(t+3<NT),(t+1<NT),(t+1<NT));       ENDW(t);   RESC(); ROT();
;     STEP(pA0,pA1,pB0,pB1,t+1,(t+4<NT),(t+2<NT),(t+2<NT));     ENDW(t+1); RESC(); ROT();
;   }
	s_cmpk_lg_i32 s42, 0x4000
	v_add_f32_e32 v64, v64, v65
	s_mov_b32 s5, s36
	s_cselect_b32 s36, s1, 0
	s_add_i32 s33, s33, 2
	v_lshl_add_u64 v[210:211], v[210:211], 0, s[22:23]
	v_lshl_add_u64 v[212:213], v[212:213], 0, s[22:23]
	s_cmp_ge_u32 s33, s89
	v_add_f32_e32 v64, v64, v74
	s_cbranch_scc0 .LBB0_311
	ds_read_b32 v230, v246
	ds_read_b32 v231, v246 offset:2048
	ds_read_b32 v232, v246 offset:4096
	ds_read_b32 v233, v246 offset:6144
	ds_read_b32 v234, v246 offset:8192
	ds_read_b32 v235, v246 offset:10240
	ds_read_b32 v236, v246 offset:12288
	ds_read_b32 v237, v246 offset:14336
	ds_read_b32 v238, v246 offset:16384
	ds_read_b32 v239, v246 offset:18432
	ds_read_b32 v240, v246 offset:20480
	ds_read_b32 v241, v246 offset:22528
	ds_read_b32 v242, v246 offset:24576
	ds_read_b32 v243, v246 offset:26624
	ds_read_b32 v244, v246 offset:28672
	ds_read_b32 v245, v246 offset:30720
	ds_read_b32 v246, v246 offset:32768
	s_waitcnt lgkmcnt(0)
	s_nop 0
	s_nop 0
	s_nop 0
	s_nop 0
	s_nop 0
	s_nop 0
	s_nop 0
	s_nop 0
	s_nop 0
	s_nop 0
	s_nop 0
	s_nop 0
	s_add_i32 s6, s4, -3
	s_branch .LBB0_314
